# all five looped GEMM K-loops: LDS-DMA loads via SGPR base + 32-bit lane offset (80 v_lshl_add_u64 removed)
# speedup vs baseline: 1.0060x; 1.0011x over previous
; #define PG8_STAGE(bufoff, gbase, voff) do { _Pragma("unroll") for (int _i = 0; _i < 2; ++_i) \
;         __builtin_amdgcn_global_load_lds((const unsigned*)((const char*)(gbase) + (voff)[_i]), (PG8_LAS unsigned*)(lds + (bufoff) + ldsw + _i * 8192), 16, 0, 0); } while (0)
; #define PG8_LDA(dst, b, h) do { _Pragma("unroll") for (int m = 0; m < 4; ++m) _Pragma("unroll") for (int k = 0; k < 2; ++k) dst[m][k] = *(const PG8_LAS bf16x8*)(lds + PG8_SA(b, h) + aoff + m * 2048 + k * 1024); } while (0)
; #define PG8_LDB(dst, b, h) do { _Pragma("unroll") for (int n = 0; n < 2; ++n) _Pragma("unroll") for (int k = 0; k < 2; ++k) dst[n][k] = *(const PG8_LAS bf16x8*)(lds + PG8_SB(b, h) + boff + n * 2048 + k * 1024); } while (0)
; #define PG8_MMA(ai, bj, At, Bt) do { __builtin_amdgcn_s_setprio(1); _Pragma("unroll") for (int m = 0; m < 4; ++m) _Pragma("unroll") for (int n = 0; n < 2; ++n) _Pragma("unroll") for (int k = 0; k < 2; ++k) \
;         acc[ai][bj][m][n] = __builtin_amdgcn_mfma_f32_16x16x32_bf16(Bt[n][k], At[m][k], acc[ai][bj][m][n], 0, 0, 0); __builtin_amdgcn_s_setprio(0); } while (0)
; #define PG8_WAIT_V(n) asm volatile("s_waitcnt vmcnt(" #n ")" ::: "memory")
; #define PG8_WAIT_L(n) asm volatile("s_waitcnt lgkmcnt(" #n ")" ::: "memory")
; #define PG8_BAR __builtin_amdgcn_s_barrier()
; #define PG8_SCHED __builtin_amdgcn_sched_barrier(0)
; template <class Epi, class Sched, bool ALIGN_EPI = false, bool SP2 = false>
; __device__ __forceinline__ void gemm_phase(PG8_LAS unsigned char* lds, int tid_in, const Gemm g, const Sched& S, const Epi& E) {
;     ...
;             PG8_LDB(B0, 0, 0); PG8_LDB(B1, 0, 1); PG8_SCHED; PG8_LDA(At, 0, 0); PG8_STAGE(PG8_SA(1, 1), a1 + hstep, voffA);
;             PG8_WAIT_V(8); PG8_WAIT_L(0); PG8_BAR; PG8_MMA(0, 0, At, B0); PG8_MMA(0, 1, At, B1); PG8_BAR; PG8_SCHED;
;             PG8_LDA(At, 0, 1); PG8_STAGE(PG8_SB(0, 0), b2, voffB); PG8_STAGE(PG8_SB(0, 1), b2 + hstep, voffB); PG8_STAGE(PG8_SA(0, 0), a2, voffA);
;             PG8_WAIT_V(8); PG8_WAIT_L(0); PG8_BAR; PG8_MMA(1, 0, At, B0); PG8_MMA(1, 1, At, B1); PG8_BAR; PG8_SCHED;
.LBB0_708:
	s_add_u32 s18, s48, 0xfffc0080
	s_addc_u32 s50, s49, -1
	s_add_i32 s64, 0, 0x10000
	s_cmp_eq_u32 s37, 12
	s_cselect_b32 s59, s17, s50
	s_cselect_b32 s58, s96, s18
	s_cselect_b32 s51, s15, s36
	s_cselect_b32 s50, s38, s39
	s_add_i32 s18, 0, 0x14000
	v_add_u32_e32 v134, s64, v228
	v_add_u32_e32 v158, s18, v228
	ds_read_b128 v[122:125], v134
	ds_read_b128 v[126:129], v134 offset:1024
	ds_read_b128 v[130:133], v134 offset:2048
	ds_read_b128 v[134:137], v134 offset:3072
	ds_read_b128 v[146:149], v158
	ds_read_b128 v[150:153], v158 offset:1024
	ds_read_b128 v[154:157], v158 offset:2048
	ds_read_b128 v[158:161], v158 offset:3072
	s_add_i32 m0, s21, 0xc000
	ds_read_b128 v[162:165], v229
	ds_read_b128 v[166:169], v229 offset:1024
	ds_read_b128 v[170:173], v229 offset:2048
	ds_read_b128 v[174:177], v229 offset:3072
	ds_read_b128 v[178:181], v229 offset:4096
	ds_read_b128 v[182:185], v229 offset:5120
	ds_read_b128 v[186:189], v229 offset:6144
	ds_read_b128 v[200:203], v229 offset:7168
	global_load_lds_dwordx4 v196, s[48:49]
	s_add_i32 m0, s21, 0xe000
	s_nop 0
	global_load_lds_dwordx4 v198, s[48:49]
	s_waitcnt vmcnt(8)
	s_waitcnt lgkmcnt(0)
	s_barrier
	s_setprio 1
	s_waitcnt lgkmcnt(0)
	v_mfma_f32_16x16x32_bf16 v[142:145], v[122:125], v[162:165], v[142:145]
	v_mfma_f32_16x16x32_bf16 v[138:141], v[130:133], v[162:165], v[138:141]
	v_mfma_f32_16x16x32_bf16 v[110:113], v[122:125], v[170:173], v[110:113]
	v_mfma_f32_16x16x32_bf16 v[106:109], v[130:133], v[170:173], v[106:109]
	v_mfma_f32_16x16x32_bf16 v[94:97], v[122:125], v[178:181], v[94:97]
	v_mfma_f32_16x16x32_bf16 v[90:93], v[130:133], v[178:181], v[90:93]
	v_mfma_f32_16x16x32_bf16 v[78:81], v[122:125], v[186:189], v[78:81]
	v_mfma_f32_16x16x32_bf16 v[74:77], v[130:133], v[186:189], v[74:77]
	v_mfma_f32_16x16x32_bf16 v[142:145], v[126:129], v[166:169], v[142:145]
	v_mfma_f32_16x16x32_bf16 v[138:141], v[134:137], v[166:169], v[138:141]
	v_mfma_f32_16x16x32_bf16 v[110:113], v[126:129], v[174:177], v[110:113]
	v_mfma_f32_16x16x32_bf16 v[106:109], v[134:137], v[174:177], v[106:109]
	v_mfma_f32_16x16x32_bf16 v[94:97], v[126:129], v[182:185], v[94:97]
	v_mfma_f32_16x16x32_bf16 v[90:93], v[134:137], v[182:185], v[90:93]
	v_mfma_f32_16x16x32_bf16 v[78:81], v[126:129], v[200:203], v[78:81]
	v_mfma_f32_16x16x32_bf16 v[74:77], v[134:137], v[200:203], v[74:77]
	v_mfma_f32_16x16x32_bf16 v[118:121], v[146:149], v[162:165], v[118:121]
	v_mfma_f32_16x16x32_bf16 v[114:117], v[154:157], v[162:165], v[114:117]
	v_mfma_f32_16x16x32_bf16 v[102:105], v[146:149], v[170:173], v[102:105]
	v_mfma_f32_16x16x32_bf16 v[98:101], v[154:157], v[170:173], v[98:101]
	v_mfma_f32_16x16x32_bf16 v[86:89], v[146:149], v[178:181], v[86:89]
	v_mfma_f32_16x16x32_bf16 v[82:85], v[154:157], v[178:181], v[82:85]
	v_mfma_f32_16x16x32_bf16 v[70:73], v[146:149], v[186:189], v[70:73]
	v_mfma_f32_16x16x32_bf16 v[66:69], v[154:157], v[186:189], v[66:69]
	v_mfma_f32_16x16x32_bf16 v[118:121], v[150:153], v[166:169], v[118:121]
	v_mfma_f32_16x16x32_bf16 v[114:117], v[158:161], v[166:169], v[114:117]
	v_mfma_f32_16x16x32_bf16 v[102:105], v[150:153], v[174:177], v[102:105]
	v_mfma_f32_16x16x32_bf16 v[98:101], v[158:161], v[174:177], v[98:101]
	v_mfma_f32_16x16x32_bf16 v[86:89], v[150:153], v[182:185], v[86:89]
	v_mfma_f32_16x16x32_bf16 v[82:85], v[158:161], v[182:185], v[82:85]
	v_mfma_f32_16x16x32_bf16 v[70:73], v[150:153], v[200:203], v[70:73]
	v_mfma_f32_16x16x32_bf16 v[66:69], v[158:161], v[200:203], v[66:69]
	s_setprio 0
	s_barrier
	s_add_i32 s64, s64, s20
	s_mov_b32 m0, s64
	ds_read_b128 v[162:165], v229 offset:16384
	ds_read_b128 v[166:169], v229 offset:17408
	ds_read_b128 v[170:173], v229 offset:18432
	ds_read_b128 v[174:177], v229 offset:19456
	ds_read_b128 v[178:181], v229 offset:20480
	ds_read_b128 v[182:185], v229 offset:21504
	ds_read_b128 v[186:189], v229 offset:22528
	ds_read_b128 v[200:203], v229 offset:23552
	global_load_lds_dwordx4 v8, s[50:51]
	s_add_i32 m0, s64, 0x2000
	s_add_u32 vcc_lo, s50, 0x40000
	s_addc_u32 vcc_hi, s51, 0
	s_add_i32 s18, s18, s20
	global_load_lds_dwordx4 v194, s[50:51]
	s_mov_b32 m0, s18
	s_nop 0
	global_load_lds_dwordx4 v8, vcc
	s_add_i32 m0, s18, 0x2000
	s_nop 0
	global_load_lds_dwordx4 v194, vcc
	s_mov_b32 m0, s21
	s_nop 0
	global_load_lds_dwordx4 v190, s[58:59]
	s_mov_b32 m0, s28
	s_nop 0
	global_load_lds_dwordx4 v192, s[58:59]
	s_waitcnt vmcnt(8)
	s_waitcnt lgkmcnt(0)
	s_barrier
	s_setprio 1
	s_waitcnt lgkmcnt(0)
	v_mfma_f32_16x16x32_bf16 v[62:65], v[122:125], v[162:165], v[62:65]
	v_mfma_f32_16x16x32_bf16 v[58:61], v[130:133], v[162:165], v[58:61]
	v_mfma_f32_16x16x32_bf16 v[46:49], v[122:125], v[170:173], v[46:49]
	v_mfma_f32_16x16x32_bf16 v[42:45], v[130:133], v[170:173], v[42:45]
	v_mfma_f32_16x16x32_bf16 v[30:33], v[122:125], v[178:181], v[30:33]
	v_mfma_f32_16x16x32_bf16 v[26:29], v[130:133], v[178:181], v[26:29]
	v_mfma_f32_16x16x32_bf16 v[14:17], v[122:125], v[186:189], v[14:17]
	v_mfma_f32_16x16x32_bf16 v[10:13], v[130:133], v[186:189], v[10:13]
	v_mfma_f32_16x16x32_bf16 v[62:65], v[126:129], v[166:169], v[62:65]
	v_mfma_f32_16x16x32_bf16 v[58:61], v[134:137], v[166:169], v[58:61]
	v_mfma_f32_16x16x32_bf16 v[46:49], v[126:129], v[174:177], v[46:49]
	v_mfma_f32_16x16x32_bf16 v[42:45], v[134:137], v[174:177], v[42:45]
	v_mfma_f32_16x16x32_bf16 v[30:33], v[126:129], v[182:185], v[30:33]
	v_mfma_f32_16x16x32_bf16 v[26:29], v[134:137], v[182:185], v[26:29]
	v_mfma_f32_16x16x32_bf16 v[14:17], v[126:129], v[200:203], v[14:17]
	v_mfma_f32_16x16x32_bf16 v[10:13], v[134:137], v[200:203], v[10:13]
	v_mfma_f32_16x16x32_bf16 v[54:57], v[146:149], v[162:165], v[54:57]
	v_mfma_f32_16x16x32_bf16 v[50:53], v[154:157], v[162:165], v[50:53]
	v_mfma_f32_16x16x32_bf16 v[38:41], v[146:149], v[170:173], v[38:41]
	v_mfma_f32_16x16x32_bf16 v[34:37], v[154:157], v[170:173], v[34:37]
	v_mfma_f32_16x16x32_bf16 v[22:25], v[146:149], v[178:181], v[22:25]
	v_mfma_f32_16x16x32_bf16 v[18:21], v[154:157], v[178:181], v[18:21]
	v_mfma_f32_16x16x32_bf16 v[4:7], v[146:149], v[186:189], v[4:7]
	v_mfma_f32_16x16x32_bf16 v[0:3], v[154:157], v[186:189], v[0:3]
	v_mfma_f32_16x16x32_bf16 v[54:57], v[150:153], v[166:169], v[54:57]
	v_mfma_f32_16x16x32_bf16 v[50:53], v[158:161], v[166:169], v[50:53]
	v_mfma_f32_16x16x32_bf16 v[38:41], v[150:153], v[174:177], v[38:41]
	v_mfma_f32_16x16x32_bf16 v[34:37], v[158:161], v[174:177], v[34:37]
	v_mfma_f32_16x16x32_bf16 v[22:25], v[150:153], v[182:185], v[22:25]
	v_mfma_f32_16x16x32_bf16 v[18:21], v[158:161], v[182:185], v[18:21]
	v_mfma_f32_16x16x32_bf16 v[4:7], v[150:153], v[200:203], v[4:7]
	v_mfma_f32_16x16x32_bf16 v[0:3], v[158:161], v[200:203], v[0:3]
	s_setprio 0
	s_barrier
; #define PG8_STAGE(bufoff, gbase, voff) do { _Pragma("unroll") for (int _i = 0; _i < 2; ++_i) \
;         __builtin_amdgcn_global_load_lds((const unsigned*)((const char*)(gbase) + (voff)[_i]), (PG8_LAS unsigned*)(lds + (bufoff) + ldsw + _i * 8192), 16, 0, 0); } while (0)
; #define PG8_LDA(dst, b, h) do { _Pragma("unroll") for (int m = 0; m < 4; ++m) _Pragma("unroll") for (int k = 0; k < 2; ++k) dst[m][k] = *(const PG8_LAS bf16x8*)(lds + PG8_SA(b, h) + aoff + m * 2048 + k * 1024); } while (0)
; #define PG8_LDB(dst, b, h) do { _Pragma("unroll") for (int n = 0; n < 2; ++n) _Pragma("unroll") for (int k = 0; k < 2; ++k) dst[n][k] = *(const PG8_LAS bf16x8*)(lds + PG8_SB(b, h) + boff + n * 2048 + k * 1024); } while (0)
; #define PG8_MMA(ai, bj, At, Bt) do { __builtin_amdgcn_s_setprio(1); _Pragma("unroll") for (int m = 0; m < 4; ++m) _Pragma("unroll") for (int n = 0; n < 2; ++n) _Pragma("unroll") for (int k = 0; k < 2; ++k) \
;         acc[ai][bj][m][n] = __builtin_amdgcn_mfma_f32_16x16x32_bf16(Bt[n][k], At[m][k], acc[ai][bj][m][n], 0, 0, 0); __builtin_amdgcn_s_setprio(0); } while (0)
; #define PG8_WAIT_V(n) asm volatile("s_waitcnt vmcnt(" #n ")" ::: "memory")
; #define PG8_WAIT_L(n) asm volatile("s_waitcnt lgkmcnt(" #n ")" ::: "memory")
; #define PG8_BAR __builtin_amdgcn_s_barrier()
; #define PG8_SCHED __builtin_amdgcn_sched_barrier(0)
; template <class Epi, class Sched, bool ALIGN_EPI = false, bool SP2 = false>
; __device__ __forceinline__ void gemm_phase(PG8_LAS unsigned char* lds, int tid_in, const Gemm g, const Sched& S, const Epi& E) {
;     ...
;             PG8_LDB(B0, 1, 0); PG8_LDB(B1, 1, 1); PG8_SCHED; PG8_LDA(At, 1, 0); PG8_STAGE(PG8_SA(0, 1), a2 + hstep, voffA);
;             PG8_WAIT_V(8); PG8_WAIT_L(0); PG8_BAR; PG8_MMA(0, 0, At, B0); PG8_MMA(0, 1, At, B1); PG8_BAR; PG8_SCHED;
	s_add_i32 s18, 0, 0x18000
	s_add_i32 s64, 0, 0x1c000
	v_add_u32_e32 v134, s18, v228
	v_add_u32_e32 v158, s64, v228
	ds_read_b128 v[122:125], v134
	ds_read_b128 v[126:129], v134 offset:1024
	ds_read_b128 v[130:133], v134 offset:2048
	ds_read_b128 v[134:137], v134 offset:3072
	ds_read_b128 v[146:149], v158
	ds_read_b128 v[150:153], v158 offset:1024
	ds_read_b128 v[154:157], v158 offset:2048
	ds_read_b128 v[158:161], v158 offset:3072
	s_add_u32 s58, s58, 0x40000
	s_addc_u32 s59, s59, 0
	s_mov_b32 m0, s29
	ds_read_b128 v[162:165], v229 offset:32768
	ds_read_b128 v[166:169], v229 offset:33792
	ds_read_b128 v[170:173], v229 offset:34816
	ds_read_b128 v[174:177], v229 offset:35840
	ds_read_b128 v[178:181], v229 offset:36864
	ds_read_b128 v[182:185], v229 offset:37888
	ds_read_b128 v[186:189], v229 offset:38912
	ds_read_b128 v[200:203], v229 offset:39936
	global_load_lds_dwordx4 v190, s[58:59]
	s_mov_b32 m0, s55
	s_nop 0
	global_load_lds_dwordx4 v192, s[58:59]
	s_waitcnt vmcnt(8)
	s_waitcnt lgkmcnt(0)
	s_barrier
	s_setprio 1
	s_waitcnt lgkmcnt(0)
	v_mfma_f32_16x16x32_bf16 v[142:145], v[122:125], v[162:165], v[142:145]
	v_mfma_f32_16x16x32_bf16 v[138:141], v[130:133], v[162:165], v[138:141]
	v_mfma_f32_16x16x32_bf16 v[110:113], v[122:125], v[170:173], v[110:113]
	v_mfma_f32_16x16x32_bf16 v[106:109], v[130:133], v[170:173], v[106:109]
	v_mfma_f32_16x16x32_bf16 v[94:97], v[122:125], v[178:181], v[94:97]
	v_mfma_f32_16x16x32_bf16 v[90:93], v[130:133], v[178:181], v[90:93]
	v_mfma_f32_16x16x32_bf16 v[78:81], v[122:125], v[186:189], v[78:81]
	v_mfma_f32_16x16x32_bf16 v[74:77], v[130:133], v[186:189], v[74:77]
	v_mfma_f32_16x16x32_bf16 v[142:145], v[126:129], v[166:169], v[142:145]
	v_mfma_f32_16x16x32_bf16 v[138:141], v[134:137], v[166:169], v[138:141]
	v_mfma_f32_16x16x32_bf16 v[110:113], v[126:129], v[174:177], v[110:113]
	v_mfma_f32_16x16x32_bf16 v[106:109], v[134:137], v[174:177], v[106:109]
	v_mfma_f32_16x16x32_bf16 v[94:97], v[126:129], v[182:185], v[94:97]
	v_mfma_f32_16x16x32_bf16 v[90:93], v[134:137], v[182:185], v[90:93]
	v_mfma_f32_16x16x32_bf16 v[78:81], v[126:129], v[200:203], v[78:81]
	v_mfma_f32_16x16x32_bf16 v[74:77], v[134:137], v[200:203], v[74:77]
	v_mfma_f32_16x16x32_bf16 v[118:121], v[146:149], v[162:165], v[118:121]
	v_mfma_f32_16x16x32_bf16 v[114:117], v[154:157], v[162:165], v[114:117]
	v_mfma_f32_16x16x32_bf16 v[102:105], v[146:149], v[170:173], v[102:105]
	v_mfma_f32_16x16x32_bf16 v[98:101], v[154:157], v[170:173], v[98:101]
	v_mfma_f32_16x16x32_bf16 v[86:89], v[146:149], v[178:181], v[86:89]
	v_mfma_f32_16x16x32_bf16 v[82:85], v[154:157], v[178:181], v[82:85]
	v_mfma_f32_16x16x32_bf16 v[70:73], v[146:149], v[186:189], v[70:73]
	v_mfma_f32_16x16x32_bf16 v[66:69], v[154:157], v[186:189], v[66:69]
	v_mfma_f32_16x16x32_bf16 v[118:121], v[150:153], v[166:169], v[118:121]
	v_mfma_f32_16x16x32_bf16 v[114:117], v[158:161], v[166:169], v[114:117]
	v_mfma_f32_16x16x32_bf16 v[102:105], v[150:153], v[174:177], v[102:105]
	v_mfma_f32_16x16x32_bf16 v[98:101], v[158:161], v[174:177], v[98:101]
	v_mfma_f32_16x16x32_bf16 v[86:89], v[150:153], v[182:185], v[86:89]
	v_mfma_f32_16x16x32_bf16 v[82:85], v[158:161], v[182:185], v[82:85]
	v_mfma_f32_16x16x32_bf16 v[70:73], v[150:153], v[200:203], v[70:73]
	v_mfma_f32_16x16x32_bf16 v[66:69], v[158:161], v[200:203], v[66:69]
	s_setprio 0
	s_barrier
; #define PG8_STAGE(bufoff, gbase, voff) do { _Pragma("unroll") for (int _i = 0; _i < 2; ++_i) \
;         __builtin_amdgcn_global_load_lds((const unsigned*)((const char*)(gbase) + (voff)[_i]), (PG8_LAS unsigned*)(lds + (bufoff) + ldsw + _i * 8192), 16, 0, 0); } while (0)
; #define PG8_LDA(dst, b, h) do { _Pragma("unroll") for (int m = 0; m < 4; ++m) _Pragma("unroll") for (int k = 0; k < 2; ++k) dst[m][k] = *(const PG8_LAS bf16x8*)(lds + PG8_SA(b, h) + aoff + m * 2048 + k * 1024); } while (0)
; #define PG8_MMA(ai, bj, At, Bt) do { __builtin_amdgcn_s_setprio(1); _Pragma("unroll") for (int m = 0; m < 4; ++m) _Pragma("unroll") for (int n = 0; n < 2; ++n) _Pragma("unroll") for (int k = 0; k < 2; ++k) \
;         acc[ai][bj][m][n] = __builtin_amdgcn_mfma_f32_16x16x32_bf16(Bt[n][k], At[m][k], acc[ai][bj][m][n], 0, 0, 0); __builtin_amdgcn_s_setprio(0); } while (0)
; #define PG8_WAIT_V(n) asm volatile("s_waitcnt vmcnt(" #n ")" ::: "memory")
; #define PG8_WAIT_L(n) asm volatile("s_waitcnt lgkmcnt(" #n ")" ::: "memory")
; #define PG8_BAR __builtin_amdgcn_s_barrier()
; #define PG8_SCHED __builtin_amdgcn_sched_barrier(0)
; template <class Epi, class Sched, bool ALIGN_EPI = false, bool SP2 = false>
; __device__ __forceinline__ void gemm_phase(PG8_LAS unsigned char* lds, int tid_in, const Gemm g, const Sched& S, const Epi& E) {
;     ...
;             PG8_LDA(At, 1, 1); PG8_STAGE(PG8_SB(1, 0), b3, voffB); PG8_STAGE(PG8_SB(1, 1), b3 + hstep, voffB); PG8_STAGE(PG8_SA(1, 0), a3, voffA);
;             PG8_WAIT_V(8); PG8_WAIT_L(0); PG8_BAR; PG8_MMA(1, 0, At, B0); PG8_MMA(1, 1, At, B1); PG8_BAR; PG8_SCHED;
;     ...
;         if constexpr (ALIGN_EPI) { if (wr == 0) PG8_BAR; }
	s_add_i32 s18, s18, s20
	s_mov_b32 m0, s18
	ds_read_b128 v[162:165], v229 offset:49152
	ds_read_b128 v[166:169], v229 offset:50176
	ds_read_b128 v[170:173], v229 offset:51200
	ds_read_b128 v[174:177], v229 offset:52224
	ds_read_b128 v[178:181], v229 offset:53248
	ds_read_b128 v[182:185], v229 offset:54272
	ds_read_b128 v[186:189], v229 offset:55296
	ds_read_b128 v[200:203], v229 offset:56320
	s_add_u32 s50, s50, 0x80
	s_addc_u32 s51, s51, 0
	global_load_lds_dwordx4 v8, s[50:51]
	s_sub_u32 s50, s50, 0x80
	s_subb_u32 s51, s51, 0
	s_add_i32 m0, s18, 0x2000
	s_add_u32 s50, s50, 0x40080
	s_addc_u32 s51, s51, 0
	s_add_i32 s18, s64, s20
	s_sub_u32 s50, s50, 0x40000
	s_subb_u32 s51, s51, 0
	global_load_lds_dwordx4 v194, s[50:51]
	s_add_u32 s50, s50, 0x40000
	s_addc_u32 s51, s51, 0
	s_mov_b32 m0, s18
	s_nop 0
	global_load_lds_dwordx4 v8, s[50:51]
	s_add_i32 m0, s18, 0x2000
	s_nop 0
	global_load_lds_dwordx4 v194, s[50:51]
	s_mov_b32 m0, s61
	s_nop 0
	s_sub_u32 s58, s58, 0x3ff80
	s_subb_u32 s59, s59, 0
	global_load_lds_dwordx4 v190, s[58:59]
	s_add_u32 s58, s58, 0x3ff80
	s_addc_u32 s59, s59, 0
	s_mov_b32 m0, s62
	s_nop 0
	s_sub_u32 s58, s58, 0x3ff80
	s_subb_u32 s59, s59, 0
	global_load_lds_dwordx4 v192, s[58:59]
	s_add_u32 s58, s58, 0x3ff80
	s_addc_u32 s59, s59, 0
	s_waitcnt vmcnt(8)
	s_waitcnt lgkmcnt(0)
	s_barrier
	s_setprio 1
	s_waitcnt lgkmcnt(0)
	v_mfma_f32_16x16x32_bf16 v[62:65], v[122:125], v[162:165], v[62:65]
	v_mfma_f32_16x16x32_bf16 v[58:61], v[130:133], v[162:165], v[58:61]
	v_mfma_f32_16x16x32_bf16 v[46:49], v[122:125], v[170:173], v[46:49]
	v_mfma_f32_16x16x32_bf16 v[42:45], v[130:133], v[170:173], v[42:45]
	v_mfma_f32_16x16x32_bf16 v[30:33], v[122:125], v[178:181], v[30:33]
	v_mfma_f32_16x16x32_bf16 v[26:29], v[130:133], v[178:181], v[26:29]
	v_mfma_f32_16x16x32_bf16 v[14:17], v[122:125], v[186:189], v[14:17]
	v_mfma_f32_16x16x32_bf16 v[10:13], v[130:133], v[186:189], v[10:13]
	v_mfma_f32_16x16x32_bf16 v[62:65], v[126:129], v[166:169], v[62:65]
	v_mfma_f32_16x16x32_bf16 v[58:61], v[134:137], v[166:169], v[58:61]
	v_mfma_f32_16x16x32_bf16 v[46:49], v[126:129], v[174:177], v[46:49]
	v_mfma_f32_16x16x32_bf16 v[42:45], v[134:137], v[174:177], v[42:45]
	v_mfma_f32_16x16x32_bf16 v[30:33], v[126:129], v[182:185], v[30:33]
	v_mfma_f32_16x16x32_bf16 v[26:29], v[134:137], v[182:185], v[26:29]
	v_mfma_f32_16x16x32_bf16 v[14:17], v[126:129], v[200:203], v[14:17]
	v_mfma_f32_16x16x32_bf16 v[10:13], v[134:137], v[200:203], v[10:13]
	v_mfma_f32_16x16x32_bf16 v[54:57], v[146:149], v[162:165], v[54:57]
	v_mfma_f32_16x16x32_bf16 v[50:53], v[154:157], v[162:165], v[50:53]
	v_mfma_f32_16x16x32_bf16 v[38:41], v[146:149], v[170:173], v[38:41]
	v_mfma_f32_16x16x32_bf16 v[34:37], v[154:157], v[170:173], v[34:37]
	v_mfma_f32_16x16x32_bf16 v[22:25], v[146:149], v[178:181], v[22:25]
	v_mfma_f32_16x16x32_bf16 v[18:21], v[154:157], v[178:181], v[18:21]
	v_mfma_f32_16x16x32_bf16 v[4:7], v[146:149], v[186:189], v[4:7]
	v_mfma_f32_16x16x32_bf16 v[0:3], v[154:157], v[186:189], v[0:3]
	v_mfma_f32_16x16x32_bf16 v[54:57], v[150:153], v[166:169], v[54:57]
	v_mfma_f32_16x16x32_bf16 v[50:53], v[158:161], v[166:169], v[50:53]
	v_mfma_f32_16x16x32_bf16 v[38:41], v[150:153], v[174:177], v[38:41]
	v_mfma_f32_16x16x32_bf16 v[34:37], v[158:161], v[174:177], v[34:37]
	v_mfma_f32_16x16x32_bf16 v[22:25], v[150:153], v[182:185], v[22:25]
	v_mfma_f32_16x16x32_bf16 v[18:21], v[158:161], v[182:185], v[18:21]
	v_mfma_f32_16x16x32_bf16 v[4:7], v[150:153], v[200:203], v[4:7]
	v_mfma_f32_16x16x32_bf16 v[0:3], v[158:161], v[200:203], v[0:3]
	s_setprio 0
	s_barrier
	s_add_i32 s37, s37, 2
	s_add_u32 s48, s48, 0x100
	s_addc_u32 s49, s49, 0
	s_add_u32 s39, s39, 0x100
	s_addc_u32 s36, s36, 0
	s_cmp_gt_u32 s37, 13
	s_cbranch_scc0 .LBB0_708
	s_and_b64 vcc, exec, s[12:13]
	s_movk_i32 s64, 0x1ff
	s_mov_b32 s96, 0x800000
	s_mov_b64 s[38:39], 0x800
	s_cbranch_vccz .LBB0_711
	s_barrier

; #define PG8_STAGE(bufoff, gbase, voff) do { _Pragma("unroll") for (int _i = 0; _i < 2; ++_i) \
;         __builtin_amdgcn_global_load_lds((const unsigned*)((const char*)(gbase) + (voff)[_i]), (PG8_LAS unsigned*)(lds + (bufoff) + ldsw + _i * 8192), 16, 0, 0); } while (0)
; #define PG8_LDA(dst, b, h) do { _Pragma("unroll") for (int m = 0; m < 4; ++m) _Pragma("unroll") for (int k = 0; k < 2; ++k) dst[m][k] = *(const PG8_LAS bf16x8*)(lds + PG8_SA(b, h) + aoff + m * 2048 + k * 1024); } while (0)
; #define PG8_LDB(dst, b, h) do { _Pragma("unroll") for (int n = 0; n < 2; ++n) _Pragma("unroll") for (int k = 0; k < 2; ++k) dst[n][k] = *(const PG8_LAS bf16x8*)(lds + PG8_SB(b, h) + boff + n * 2048 + k * 1024); } while (0)
; #define PG8_MMA(ai, bj, At, Bt) do { __builtin_amdgcn_s_setprio(1); _Pragma("unroll") for (int m = 0; m < 4; ++m) _Pragma("unroll") for (int n = 0; n < 2; ++n) _Pragma("unroll") for (int k = 0; k < 2; ++k) \
;         acc[ai][bj][m][n] = __builtin_amdgcn_mfma_f32_16x16x32_bf16(Bt[n][k], At[m][k], acc[ai][bj][m][n], 0, 0, 0); __builtin_amdgcn_s_setprio(0); } while (0)
; #define PG8_WAIT_V(n) asm volatile("s_waitcnt vmcnt(" #n ")" ::: "memory")
; #define PG8_WAIT_L(n) asm volatile("s_waitcnt lgkmcnt(" #n ")" ::: "memory")
; #define PG8_BAR __builtin_amdgcn_s_barrier()
; #define PG8_SCHED __builtin_amdgcn_sched_barrier(0)
; template <class Epi, class Sched, bool ALIGN_EPI = false, bool SP2 = false>
; __device__ __forceinline__ void gemm_phase(PG8_LAS unsigned char* lds, int tid_in, const Gemm g, const Sched& S, const Epi& E) {
;     ...
;             PG8_LDB(B0, 0, 0); PG8_LDB(B1, 0, 1); PG8_SCHED; PG8_LDA(At, 0, 0); PG8_STAGE(PG8_SA(1, 1), a1 + hstep, voffA);
;             PG8_WAIT_V(8); PG8_WAIT_L(0); PG8_BAR; PG8_MMA(0, 0, At, B0); PG8_MMA(0, 1, At, B1); PG8_BAR; PG8_SCHED;
;             PG8_LDA(At, 0, 1); PG8_STAGE(PG8_SB(0, 0), b2, voffB); PG8_STAGE(PG8_SB(0, 1), b2 + hstep, voffB); PG8_STAGE(PG8_SA(0, 0), a2, voffA);
;             PG8_WAIT_V(8); PG8_WAIT_L(0); PG8_BAR; PG8_MMA(1, 0, At, B0); PG8_MMA(1, 1, At, B1); PG8_BAR; PG8_SCHED;
.LBB0_915:
	s_add_u32 s8, s6, 0xfff00080
	s_addc_u32 s9, s7, -1
	s_add_i32 s64, 0, 0x10000
	s_cmp_eq_u32 s18, 60
	s_cselect_b32 vcc_hi, s59, s9
	s_cselect_b32 vcc_lo, s38, s8
	s_cselect_b32 s9, s39, s37
	s_cselect_b32 s8, s43, s36
	s_add_i32 s66, 0, 0x14000
	v_add_u32_e32 v126, s64, v245
	v_add_u32_e32 v150, s66, v245
	ds_read_b128 v[110:113], v126
	ds_read_b128 v[118:121], v126 offset:1024
	ds_read_b128 v[122:125], v126 offset:2048
	ds_read_b128 v[126:129], v126 offset:3072
	ds_read_b128 v[134:137], v150
	ds_read_b128 v[142:145], v150 offset:1024
	ds_read_b128 v[146:149], v150 offset:2048
	ds_read_b128 v[150:153], v150 offset:3072
	s_add_i32 m0, s49, 0xc000
	ds_read_b128 v[154:157], v247
	ds_read_b128 v[166:169], v247 offset:1024
	ds_read_b128 v[170:173], v247 offset:2048
	ds_read_b128 v[174:177], v247 offset:3072
	ds_read_b128 v[178:181], v247 offset:4096
	ds_read_b128 v[182:185], v247 offset:5120
	ds_read_b128 v[186:189], v247 offset:6144
	ds_read_b128 v[190:193], v247 offset:7168
	global_load_lds_dwordx4 v224, s[6:7]
	s_add_i32 m0, s49, 0xe000
	s_nop 0
	global_load_lds_dwordx4 v226, s[6:7]
	s_waitcnt vmcnt(8)
	s_waitcnt lgkmcnt(0)
	s_barrier
	s_setprio 1
	s_waitcnt lgkmcnt(0)
	v_mfma_f32_16x16x32_bf16 v[162:165], v[110:113], v[154:157], v[162:165]
	v_mfma_f32_16x16x32_bf16 v[158:161], v[122:125], v[154:157], v[158:161]
	v_mfma_f32_16x16x32_bf16 v[114:117], v[110:113], v[170:173], v[114:117]
	v_mfma_f32_16x16x32_bf16 v[106:109], v[122:125], v[170:173], v[106:109]
	v_mfma_f32_16x16x32_bf16 v[94:97], v[110:113], v[178:181], v[94:97]
	v_mfma_f32_16x16x32_bf16 v[90:93], v[122:125], v[178:181], v[90:93]
	v_mfma_f32_16x16x32_bf16 v[78:81], v[110:113], v[186:189], v[78:81]
	v_mfma_f32_16x16x32_bf16 v[74:77], v[122:125], v[186:189], v[74:77]
	v_mfma_f32_16x16x32_bf16 v[162:165], v[118:121], v[166:169], v[162:165]
	v_mfma_f32_16x16x32_bf16 v[158:161], v[126:129], v[166:169], v[158:161]
	v_mfma_f32_16x16x32_bf16 v[114:117], v[118:121], v[174:177], v[114:117]
	v_mfma_f32_16x16x32_bf16 v[106:109], v[126:129], v[174:177], v[106:109]
	v_mfma_f32_16x16x32_bf16 v[94:97], v[118:121], v[182:185], v[94:97]
	v_mfma_f32_16x16x32_bf16 v[90:93], v[126:129], v[182:185], v[90:93]
	v_mfma_f32_16x16x32_bf16 v[78:81], v[118:121], v[190:193], v[78:81]
	v_mfma_f32_16x16x32_bf16 v[74:77], v[126:129], v[190:193], v[74:77]
	v_mfma_f32_16x16x32_bf16 v[138:141], v[134:137], v[154:157], v[138:141]
	v_mfma_f32_16x16x32_bf16 v[130:133], v[146:149], v[154:157], v[130:133]
	v_mfma_f32_16x16x32_bf16 v[102:105], v[134:137], v[170:173], v[102:105]
	v_mfma_f32_16x16x32_bf16 v[98:101], v[146:149], v[170:173], v[98:101]
	v_mfma_f32_16x16x32_bf16 v[86:89], v[134:137], v[178:181], v[86:89]
	v_mfma_f32_16x16x32_bf16 v[82:85], v[146:149], v[178:181], v[82:85]
	v_mfma_f32_16x16x32_bf16 v[70:73], v[134:137], v[186:189], v[70:73]
	v_mfma_f32_16x16x32_bf16 v[66:69], v[146:149], v[186:189], v[66:69]
	v_mfma_f32_16x16x32_bf16 v[138:141], v[142:145], v[166:169], v[138:141]
	v_mfma_f32_16x16x32_bf16 v[130:133], v[150:153], v[166:169], v[130:133]
	v_mfma_f32_16x16x32_bf16 v[102:105], v[142:145], v[174:177], v[102:105]
	v_mfma_f32_16x16x32_bf16 v[98:101], v[150:153], v[174:177], v[98:101]
	v_mfma_f32_16x16x32_bf16 v[86:89], v[142:145], v[182:185], v[86:89]
	v_mfma_f32_16x16x32_bf16 v[82:85], v[150:153], v[182:185], v[82:85]
	v_mfma_f32_16x16x32_bf16 v[70:73], v[142:145], v[190:193], v[70:73]
	v_mfma_f32_16x16x32_bf16 v[66:69], v[150:153], v[190:193], v[66:69]
	s_setprio 0
	s_barrier
	s_add_i32 s64, s64, s55
	s_mov_b32 m0, s64
	ds_read_b128 v[154:157], v247 offset:16384
	ds_read_b128 v[166:169], v247 offset:17408
	ds_read_b128 v[170:173], v247 offset:18432
	ds_read_b128 v[174:177], v247 offset:19456
	ds_read_b128 v[178:181], v247 offset:20480
	ds_read_b128 v[182:185], v247 offset:21504
	ds_read_b128 v[186:189], v247 offset:22528
	ds_read_b128 v[190:193], v247 offset:23552
	global_load_lds_dwordx4 v8, s[8:9]
	s_add_i32 m0, s64, 0x2000
	s_add_u32 s64, s8, 0x100000
	s_addc_u32 s65, s9, 0
	s_add_i32 s66, s66, s55
	global_load_lds_dwordx4 v222, s[8:9]
	s_mov_b32 m0, s66
	s_nop 0
	global_load_lds_dwordx4 v8, s[64:65]
	s_add_i32 m0, s66, 0x2000
	s_nop 0
	global_load_lds_dwordx4 v222, s[64:65]
	s_mov_b32 m0, s49
	s_nop 0
	global_load_lds_dwordx4 v218, vcc
	s_mov_b32 m0, s62
	s_nop 0
	global_load_lds_dwordx4 v220, vcc
	s_waitcnt vmcnt(8)
	s_waitcnt lgkmcnt(0)
	s_barrier
	s_setprio 1
	s_waitcnt lgkmcnt(0)
	v_mfma_f32_16x16x32_bf16 v[62:65], v[110:113], v[154:157], v[62:65]
	v_mfma_f32_16x16x32_bf16 v[58:61], v[122:125], v[154:157], v[58:61]
	v_mfma_f32_16x16x32_bf16 v[46:49], v[110:113], v[170:173], v[46:49]
	v_mfma_f32_16x16x32_bf16 v[42:45], v[122:125], v[170:173], v[42:45]
	v_mfma_f32_16x16x32_bf16 v[30:33], v[110:113], v[178:181], v[30:33]
	v_mfma_f32_16x16x32_bf16 v[26:29], v[122:125], v[178:181], v[26:29]
	v_mfma_f32_16x16x32_bf16 v[14:17], v[110:113], v[186:189], v[14:17]
	v_mfma_f32_16x16x32_bf16 v[10:13], v[122:125], v[186:189], v[10:13]
	v_mfma_f32_16x16x32_bf16 v[62:65], v[118:121], v[166:169], v[62:65]
	v_mfma_f32_16x16x32_bf16 v[58:61], v[126:129], v[166:169], v[58:61]
	v_mfma_f32_16x16x32_bf16 v[46:49], v[118:121], v[174:177], v[46:49]
	v_mfma_f32_16x16x32_bf16 v[42:45], v[126:129], v[174:177], v[42:45]
	v_mfma_f32_16x16x32_bf16 v[30:33], v[118:121], v[182:185], v[30:33]
	v_mfma_f32_16x16x32_bf16 v[26:29], v[126:129], v[182:185], v[26:29]
	v_mfma_f32_16x16x32_bf16 v[14:17], v[118:121], v[190:193], v[14:17]
	v_mfma_f32_16x16x32_bf16 v[10:13], v[126:129], v[190:193], v[10:13]
	v_mfma_f32_16x16x32_bf16 v[54:57], v[134:137], v[154:157], v[54:57]
	v_mfma_f32_16x16x32_bf16 v[50:53], v[146:149], v[154:157], v[50:53]
	v_mfma_f32_16x16x32_bf16 v[38:41], v[134:137], v[170:173], v[38:41]
	v_mfma_f32_16x16x32_bf16 v[34:37], v[146:149], v[170:173], v[34:37]
	v_mfma_f32_16x16x32_bf16 v[22:25], v[134:137], v[178:181], v[22:25]
	v_mfma_f32_16x16x32_bf16 v[18:21], v[146:149], v[178:181], v[18:21]
	v_mfma_f32_16x16x32_bf16 v[4:7], v[134:137], v[186:189], v[4:7]
	v_mfma_f32_16x16x32_bf16 v[0:3], v[146:149], v[186:189], v[0:3]
	v_mfma_f32_16x16x32_bf16 v[54:57], v[142:145], v[166:169], v[54:57]
	v_mfma_f32_16x16x32_bf16 v[50:53], v[150:153], v[166:169], v[50:53]
	v_mfma_f32_16x16x32_bf16 v[38:41], v[142:145], v[174:177], v[38:41]
	v_mfma_f32_16x16x32_bf16 v[34:37], v[150:153], v[174:177], v[34:37]
	v_mfma_f32_16x16x32_bf16 v[22:25], v[142:145], v[182:185], v[22:25]
	v_mfma_f32_16x16x32_bf16 v[18:21], v[150:153], v[182:185], v[18:21]
	v_mfma_f32_16x16x32_bf16 v[4:7], v[142:145], v[190:193], v[4:7]
	v_mfma_f32_16x16x32_bf16 v[0:3], v[150:153], v[190:193], v[0:3]
	s_setprio 0
	s_barrier
; #define PG8_STAGE(bufoff, gbase, voff) do { _Pragma("unroll") for (int _i = 0; _i < 2; ++_i) \
;         __builtin_amdgcn_global_load_lds((const unsigned*)((const char*)(gbase) + (voff)[_i]), (PG8_LAS unsigned*)(lds + (bufoff) + ldsw + _i * 8192), 16, 0, 0); } while (0)
; #define PG8_LDA(dst, b, h) do { _Pragma("unroll") for (int m = 0; m < 4; ++m) _Pragma("unroll") for (int k = 0; k < 2; ++k) dst[m][k] = *(const PG8_LAS bf16x8*)(lds + PG8_SA(b, h) + aoff + m * 2048 + k * 1024); } while (0)
; #define PG8_LDB(dst, b, h) do { _Pragma("unroll") for (int n = 0; n < 2; ++n) _Pragma("unroll") for (int k = 0; k < 2; ++k) dst[n][k] = *(const PG8_LAS bf16x8*)(lds + PG8_SB(b, h) + boff + n * 2048 + k * 1024); } while (0)
; #define PG8_MMA(ai, bj, At, Bt) do { __builtin_amdgcn_s_setprio(1); _Pragma("unroll") for (int m = 0; m < 4; ++m) _Pragma("unroll") for (int n = 0; n < 2; ++n) _Pragma("unroll") for (int k = 0; k < 2; ++k) \
;         acc[ai][bj][m][n] = __builtin_amdgcn_mfma_f32_16x16x32_bf16(Bt[n][k], At[m][k], acc[ai][bj][m][n], 0, 0, 0); __builtin_amdgcn_s_setprio(0); } while (0)
; #define PG8_WAIT_V(n) asm volatile("s_waitcnt vmcnt(" #n ")" ::: "memory")
; #define PG8_WAIT_L(n) asm volatile("s_waitcnt lgkmcnt(" #n ")" ::: "memory")
; #define PG8_BAR __builtin_amdgcn_s_barrier()
; #define PG8_SCHED __builtin_amdgcn_sched_barrier(0)
; template <class Epi, class Sched, bool ALIGN_EPI = false, bool SP2 = false>
; __device__ __forceinline__ void gemm_phase(PG8_LAS unsigned char* lds, int tid_in, const Gemm g, const Sched& S, const Epi& E) {
;     ...
;             PG8_LDB(B0, 1, 0); PG8_LDB(B1, 1, 1); PG8_SCHED; PG8_LDA(At, 1, 0); PG8_STAGE(PG8_SA(0, 1), a2 + hstep, voffA);
;             PG8_WAIT_V(8); PG8_WAIT_L(0); PG8_BAR; PG8_MMA(0, 0, At, B0); PG8_MMA(0, 1, At, B1); PG8_BAR; PG8_SCHED;
	s_add_i32 s66, 0, 0x18000
	s_add_i32 s67, 0, 0x1c000
	v_add_u32_e32 v126, s66, v245
	v_add_u32_e32 v150, s67, v245
	ds_read_b128 v[110:113], v126
	ds_read_b128 v[118:121], v126 offset:1024
	ds_read_b128 v[122:125], v126 offset:2048
	ds_read_b128 v[126:129], v126 offset:3072
	ds_read_b128 v[134:137], v150
	ds_read_b128 v[142:145], v150 offset:1024
	ds_read_b128 v[146:149], v150 offset:2048
	ds_read_b128 v[150:153], v150 offset:3072
	s_add_u32 s64, vcc_lo, 0x100000
	s_addc_u32 s65, vcc_hi, 0
	s_mov_b32 m0, s63
	ds_read_b128 v[154:157], v247 offset:32768
	ds_read_b128 v[166:169], v247 offset:33792
	ds_read_b128 v[170:173], v247 offset:34816
	ds_read_b128 v[174:177], v247 offset:35840
	ds_read_b128 v[178:181], v247 offset:36864
	ds_read_b128 v[182:185], v247 offset:37888
	ds_read_b128 v[186:189], v247 offset:38912
	ds_read_b128 v[190:193], v247 offset:39936
	global_load_lds_dwordx4 v218, s[64:65]
	s_mov_b32 m0, s0
	s_nop 0
	global_load_lds_dwordx4 v220, s[64:65]
	s_waitcnt vmcnt(8)
	s_waitcnt lgkmcnt(0)
	s_barrier
	s_setprio 1
	s_waitcnt lgkmcnt(0)
	v_mfma_f32_16x16x32_bf16 v[162:165], v[110:113], v[154:157], v[162:165]
	v_mfma_f32_16x16x32_bf16 v[158:161], v[122:125], v[154:157], v[158:161]
	v_mfma_f32_16x16x32_bf16 v[114:117], v[110:113], v[170:173], v[114:117]
	v_mfma_f32_16x16x32_bf16 v[106:109], v[122:125], v[170:173], v[106:109]
	v_mfma_f32_16x16x32_bf16 v[94:97], v[110:113], v[178:181], v[94:97]
	v_mfma_f32_16x16x32_bf16 v[90:93], v[122:125], v[178:181], v[90:93]
	v_mfma_f32_16x16x32_bf16 v[78:81], v[110:113], v[186:189], v[78:81]
	v_mfma_f32_16x16x32_bf16 v[74:77], v[122:125], v[186:189], v[74:77]
	v_mfma_f32_16x16x32_bf16 v[162:165], v[118:121], v[166:169], v[162:165]
	v_mfma_f32_16x16x32_bf16 v[158:161], v[126:129], v[166:169], v[158:161]
	v_mfma_f32_16x16x32_bf16 v[114:117], v[118:121], v[174:177], v[114:117]
	v_mfma_f32_16x16x32_bf16 v[106:109], v[126:129], v[174:177], v[106:109]
	v_mfma_f32_16x16x32_bf16 v[94:97], v[118:121], v[182:185], v[94:97]
	v_mfma_f32_16x16x32_bf16 v[90:93], v[126:129], v[182:185], v[90:93]
	v_mfma_f32_16x16x32_bf16 v[78:81], v[118:121], v[190:193], v[78:81]
	v_mfma_f32_16x16x32_bf16 v[74:77], v[126:129], v[190:193], v[74:77]
	v_mfma_f32_16x16x32_bf16 v[138:141], v[134:137], v[154:157], v[138:141]
	v_mfma_f32_16x16x32_bf16 v[130:133], v[146:149], v[154:157], v[130:133]
	v_mfma_f32_16x16x32_bf16 v[102:105], v[134:137], v[170:173], v[102:105]
	v_mfma_f32_16x16x32_bf16 v[98:101], v[146:149], v[170:173], v[98:101]
	v_mfma_f32_16x16x32_bf16 v[86:89], v[134:137], v[178:181], v[86:89]
	v_mfma_f32_16x16x32_bf16 v[82:85], v[146:149], v[178:181], v[82:85]
	v_mfma_f32_16x16x32_bf16 v[70:73], v[134:137], v[186:189], v[70:73]
	v_mfma_f32_16x16x32_bf16 v[66:69], v[146:149], v[186:189], v[66:69]
	v_mfma_f32_16x16x32_bf16 v[138:141], v[142:145], v[166:169], v[138:141]
	v_mfma_f32_16x16x32_bf16 v[130:133], v[150:153], v[166:169], v[130:133]
	v_mfma_f32_16x16x32_bf16 v[102:105], v[142:145], v[174:177], v[102:105]
	v_mfma_f32_16x16x32_bf16 v[98:101], v[150:153], v[174:177], v[98:101]
	v_mfma_f32_16x16x32_bf16 v[86:89], v[142:145], v[182:185], v[86:89]
	v_mfma_f32_16x16x32_bf16 v[82:85], v[150:153], v[182:185], v[82:85]
	v_mfma_f32_16x16x32_bf16 v[70:73], v[142:145], v[190:193], v[70:73]
	v_mfma_f32_16x16x32_bf16 v[66:69], v[150:153], v[190:193], v[66:69]
	s_setprio 0
	s_barrier
; #define PG8_STAGE(bufoff, gbase, voff) do { _Pragma("unroll") for (int _i = 0; _i < 2; ++_i) \
;         __builtin_amdgcn_global_load_lds((const unsigned*)((const char*)(gbase) + (voff)[_i]), (PG8_LAS unsigned*)(lds + (bufoff) + ldsw + _i * 8192), 16, 0, 0); } while (0)
; #define PG8_LDA(dst, b, h) do { _Pragma("unroll") for (int m = 0; m < 4; ++m) _Pragma("unroll") for (int k = 0; k < 2; ++k) dst[m][k] = *(const PG8_LAS bf16x8*)(lds + PG8_SA(b, h) + aoff + m * 2048 + k * 1024); } while (0)
; #define PG8_MMA(ai, bj, At, Bt) do { __builtin_amdgcn_s_setprio(1); _Pragma("unroll") for (int m = 0; m < 4; ++m) _Pragma("unroll") for (int n = 0; n < 2; ++n) _Pragma("unroll") for (int k = 0; k < 2; ++k) \
;         acc[ai][bj][m][n] = __builtin_amdgcn_mfma_f32_16x16x32_bf16(Bt[n][k], At[m][k], acc[ai][bj][m][n], 0, 0, 0); __builtin_amdgcn_s_setprio(0); } while (0)
; #define PG8_WAIT_V(n) asm volatile("s_waitcnt vmcnt(" #n ")" ::: "memory")
; #define PG8_WAIT_L(n) asm volatile("s_waitcnt lgkmcnt(" #n ")" ::: "memory")
; #define PG8_BAR __builtin_amdgcn_s_barrier()
; #define PG8_SCHED __builtin_amdgcn_sched_barrier(0)
; template <class Epi, class Sched, bool ALIGN_EPI = false, bool SP2 = false>
; __device__ __forceinline__ void gemm_phase(PG8_LAS unsigned char* lds, int tid_in, const Gemm g, const Sched& S, const Epi& E) {
;     ...
;         for (int t = 0; t < nt; t += 2) {
;     ...
;             PG8_LDA(At, 1, 1); PG8_STAGE(PG8_SB(1, 0), b3, voffB); PG8_STAGE(PG8_SB(1, 1), b3 + hstep, voffB); PG8_STAGE(PG8_SA(1, 0), a3, voffA);
;             PG8_WAIT_V(8); PG8_WAIT_L(0); PG8_BAR; PG8_MMA(1, 0, At, B0); PG8_MMA(1, 1, At, B1); PG8_BAR; PG8_SCHED;
	s_add_i32 s64, s66, s55
	s_mov_b32 m0, s64
	ds_read_b128 v[154:157], v247 offset:49152
	ds_read_b128 v[166:169], v247 offset:50176
	ds_read_b128 v[170:173], v247 offset:51200
	ds_read_b128 v[174:177], v247 offset:52224
	ds_read_b128 v[178:181], v247 offset:53248
	ds_read_b128 v[182:185], v247 offset:54272
	ds_read_b128 v[186:189], v247 offset:55296
	ds_read_b128 v[190:193], v247 offset:56320
	s_add_u32 s8, s8, 0x80
	s_addc_u32 s9, s9, 0
	global_load_lds_dwordx4 v8, s[8:9]
	s_sub_u32 s8, s8, 0x80
	s_subb_u32 s9, s9, 0
	s_add_i32 m0, s64, 0x2000
	s_add_u32 s8, s8, 0x100080
	s_addc_u32 s9, s9, 0
	s_add_i32 s64, s67, s55
	s_sub_u32 s8, s8, 0x100000
	s_subb_u32 s9, s9, 0
	global_load_lds_dwordx4 v222, s[8:9]
	s_add_u32 s8, s8, 0x100000
	s_addc_u32 s9, s9, 0
	s_mov_b32 m0, s64
	s_nop 0
	global_load_lds_dwordx4 v8, s[8:9]
	s_add_i32 m0, s64, 0x2000
	s_nop 0
	global_load_lds_dwordx4 v222, s[8:9]
	s_mov_b32 m0, s21
	s_nop 0
	s_add_u32 vcc_lo, vcc_lo, 0x80
	s_addc_u32 vcc_hi, vcc_hi, 0
	global_load_lds_dwordx4 v218, vcc
	s_sub_u32 vcc_lo, vcc_lo, 0x80
	s_subb_u32 vcc_hi, vcc_hi, 0
	s_mov_b32 m0, s96
	s_nop 0
	s_add_u32 vcc_lo, vcc_lo, 0x80
	s_addc_u32 vcc_hi, vcc_hi, 0
	global_load_lds_dwordx4 v220, vcc
	s_sub_u32 vcc_lo, vcc_lo, 0x80
	s_subb_u32 vcc_hi, vcc_hi, 0
	s_waitcnt vmcnt(8)
	s_waitcnt lgkmcnt(0)
	s_barrier
	s_setprio 1
	s_waitcnt lgkmcnt(0)
	v_mfma_f32_16x16x32_bf16 v[62:65], v[110:113], v[154:157], v[62:65]
	v_mfma_f32_16x16x32_bf16 v[58:61], v[122:125], v[154:157], v[58:61]
	v_mfma_f32_16x16x32_bf16 v[46:49], v[110:113], v[170:173], v[46:49]
	v_mfma_f32_16x16x32_bf16 v[42:45], v[122:125], v[170:173], v[42:45]
	v_mfma_f32_16x16x32_bf16 v[30:33], v[110:113], v[178:181], v[30:33]
	v_mfma_f32_16x16x32_bf16 v[26:29], v[122:125], v[178:181], v[26:29]
	v_mfma_f32_16x16x32_bf16 v[14:17], v[110:113], v[186:189], v[14:17]
	v_mfma_f32_16x16x32_bf16 v[10:13], v[122:125], v[186:189], v[10:13]
	v_mfma_f32_16x16x32_bf16 v[62:65], v[118:121], v[166:169], v[62:65]
	v_mfma_f32_16x16x32_bf16 v[58:61], v[126:129], v[166:169], v[58:61]
	v_mfma_f32_16x16x32_bf16 v[46:49], v[118:121], v[174:177], v[46:49]
	v_mfma_f32_16x16x32_bf16 v[42:45], v[126:129], v[174:177], v[42:45]
	v_mfma_f32_16x16x32_bf16 v[30:33], v[118:121], v[182:185], v[30:33]
	v_mfma_f32_16x16x32_bf16 v[26:29], v[126:129], v[182:185], v[26:29]
	v_mfma_f32_16x16x32_bf16 v[14:17], v[118:121], v[190:193], v[14:17]
	v_mfma_f32_16x16x32_bf16 v[10:13], v[126:129], v[190:193], v[10:13]
	v_mfma_f32_16x16x32_bf16 v[54:57], v[134:137], v[154:157], v[54:57]
	v_mfma_f32_16x16x32_bf16 v[50:53], v[146:149], v[154:157], v[50:53]
	v_mfma_f32_16x16x32_bf16 v[38:41], v[134:137], v[170:173], v[38:41]
	v_mfma_f32_16x16x32_bf16 v[34:37], v[146:149], v[170:173], v[34:37]
	v_mfma_f32_16x16x32_bf16 v[22:25], v[134:137], v[178:181], v[22:25]
	v_mfma_f32_16x16x32_bf16 v[18:21], v[146:149], v[178:181], v[18:21]
	v_mfma_f32_16x16x32_bf16 v[4:7], v[134:137], v[186:189], v[4:7]
	v_mfma_f32_16x16x32_bf16 v[0:3], v[146:149], v[186:189], v[0:3]
	v_mfma_f32_16x16x32_bf16 v[54:57], v[142:145], v[166:169], v[54:57]
	v_mfma_f32_16x16x32_bf16 v[50:53], v[150:153], v[166:169], v[50:53]
	v_mfma_f32_16x16x32_bf16 v[38:41], v[142:145], v[174:177], v[38:41]
	v_mfma_f32_16x16x32_bf16 v[34:37], v[150:153], v[174:177], v[34:37]
	v_mfma_f32_16x16x32_bf16 v[22:25], v[142:145], v[182:185], v[22:25]
	v_mfma_f32_16x16x32_bf16 v[18:21], v[150:153], v[182:185], v[18:21]
	v_mfma_f32_16x16x32_bf16 v[4:7], v[142:145], v[190:193], v[4:7]
	v_mfma_f32_16x16x32_bf16 v[0:3], v[150:153], v[190:193], v[0:3]
	s_setprio 0
	s_barrier
	s_add_i32 s18, s18, 2
	s_add_u32 s6, s6, 0x100
	s_addc_u32 s7, s7, 0
	s_add_u32 s36, s36, 0x100
	s_addc_u32 s37, s37, 0
	s_cmp_gt_u32 s18, 61
	s_cbranch_scc0 .LBB0_915
	s_and_b64 vcc, exec, s[34:35]
	s_cbranch_vccz .LBB0_918
	s_barrier
